# grid barriers, local waiters: 3-deep pipelined generation poll (a new sc1 load every third of a round trip), in-flight polls not drained at exit
# speedup vs baseline: 1.0017x; 1.0017x over previous
; __device__ __forceinline__ unsigned xb_ld(unsigned* p)              { return __hip_atomic_load(p, __ATOMIC_RELAXED, __HIP_MEMORY_SCOPE_AGENT); }
; #define XB_SPIN(cond, bar) do { unsigned _sp = 0; while (cond) { __builtin_amdgcn_s_sleep(1); \
;     if ((++_sp & 255u) == 0u) { if (xb_ld(&(bar)[XB_TMO])) break; if (_sp > XB_SPIN_CAP) { atomicAdd(&(bar)[XB_TMO], 1u); break; } } } } while (0)
; __device__ __forceinline__ void xcd_barrier(const XcdBarrier& b) {
;     ...
;         } else {
;             XB_SPIN(xb_ld(&bar[XB_XGEN(b.x)]) == gen, bar);
;             __builtin_amdgcn_fence(__ATOMIC_ACQUIRE, "agent");
;             asm volatile("s_waitcnt vmcnt(0)" ::: "memory");
;         }
.LBB0_88:
	s_or_b64 exec, exec, s[8:9]
	v_cvt_f32_u32_e32 v4, v2
	s_waitcnt vmcnt(0)
	v_readfirstlane_b32 s6, v3
	v_sub_u32_e32 v3, 0, v2
	v_rcp_iflag_f32_e32 v4, v4
	v_add_u32_e32 v5, s6, v1
	v_mul_f32_e32 v4, 0x4f7ffffe, v4
	v_cvt_u32_f32_e32 v4, v4
	v_mul_lo_u32 v1, v3, v4
	v_mul_hi_u32 v1, v4, v1
	v_add_u32_e32 v1, v4, v1
	v_mul_hi_u32 v1, v5, v1
	v_mul_lo_u32 v3, v1, v2
	v_sub_u32_e32 v3, v5, v3
	v_add_u32_e32 v4, 1, v1
	v_cmp_ge_u32_e32 vcc, v3, v2
	s_nop 1
	v_cndmask_b32_e32 v1, v1, v4, vcc
	v_sub_u32_e32 v4, v3, v2
	v_cndmask_b32_e32 v3, v3, v4, vcc
	v_add_u32_e32 v4, 1, v1
	v_cmp_ge_u32_e32 vcc, v3, v2
	v_add_u32_e32 v3, 1, v5
	s_nop 0
	v_cndmask_b32_e32 v1, v1, v4, vcc
	v_mul_lo_u32 v4, v2, v1
	v_add_u32_e32 v2, v4, v2
	v_cmp_ne_u32_e32 vcc, v3, v2
	s_and_saveexec_b64 s[6:7], vcc
	s_xor_b64 s[6:7], exec, s[6:7]
	s_cbranch_execz .LBB0_102
	s_waitcnt lgkmcnt(0)
	s_mov_b64 s[8:9], exec
	s_add_u32 s12, s96, 0x183500
	s_addc_u32 s13, s97, 0
	v_mov_b32_e32 v0, 0
	buffer_inv sc1
	s_mov_b32 s24, 0x100000
	global_load_dword v120, v0, s[12:13] sc1
	s_sleep 5
	global_load_dword v121, v0, s[12:13] sc1
	s_sleep 5
.Lpl_b1_loop:
	global_load_dword v122, v0, s[12:13] sc1
	s_waitcnt vmcnt(2)
	v_cmp_ne_u32_e32 vcc, v120, v1
	s_cbranch_vccnz .Lpl_b1_done
	s_sleep 5
	global_load_dword v120, v0, s[12:13] sc1
	s_waitcnt vmcnt(2)
	v_cmp_ne_u32_e32 vcc, v121, v1
	s_cbranch_vccnz .Lpl_b1_done
	s_sleep 5
	global_load_dword v121, v0, s[12:13] sc1
	s_waitcnt vmcnt(2)
	v_cmp_ne_u32_e32 vcc, v122, v1
	s_cbranch_vccnz .Lpl_b1_done
	s_sleep 5
	s_sub_i32 s24, s24, 1
	s_cmp_lg_u32 s24, 0
	s_cbranch_scc1 .Lpl_b1_loop
.Lpl_b1_done:
.LBB0_101:
	s_or_b64 exec, exec, s[8:9]

; __device__ __forceinline__ unsigned xb_ld(unsigned* p)              { return __hip_atomic_load(p, __ATOMIC_RELAXED, __HIP_MEMORY_SCOPE_AGENT); }
; #define XB_SPIN(cond, bar) do { unsigned _sp = 0; while (cond) { __builtin_amdgcn_s_sleep(1); \
;     if ((++_sp & 255u) == 0u) { if (xb_ld(&(bar)[XB_TMO])) break; if (_sp > XB_SPIN_CAP) { atomicAdd(&(bar)[XB_TMO], 1u); break; } } } } while (0)
; __device__ __forceinline__ void xcd_barrier(const XcdBarrier& b) {
;     ...
;         } else {
;             XB_SPIN(xb_ld(&bar[XB_XGEN(b.x)]) == gen, bar);
;             __builtin_amdgcn_fence(__ATOMIC_ACQUIRE, "agent");
;             asm volatile("s_waitcnt vmcnt(0)" ::: "memory");
;         }
.LBB0_357:
	s_or_b64 exec, exec, s[6:7]
	v_cvt_f32_u32_e32 v4, v2
	s_waitcnt vmcnt(0)
	v_readfirstlane_b32 s4, v3
	v_sub_u32_e32 v3, 0, v2
	v_rcp_iflag_f32_e32 v4, v4
	v_add_u32_e32 v5, s4, v1
	v_mul_f32_e32 v4, 0x4f7ffffe, v4
	v_cvt_u32_f32_e32 v4, v4
	v_mul_lo_u32 v1, v3, v4
	v_mul_hi_u32 v1, v4, v1
	v_add_u32_e32 v1, v4, v1
	v_mul_hi_u32 v1, v5, v1
	v_mul_lo_u32 v3, v1, v2
	v_sub_u32_e32 v3, v5, v3
	v_add_u32_e32 v4, 1, v1
	v_cmp_ge_u32_e32 vcc, v3, v2
	s_nop 1
	v_cndmask_b32_e32 v1, v1, v4, vcc
	v_sub_u32_e32 v4, v3, v2
	v_cndmask_b32_e32 v3, v3, v4, vcc
	v_add_u32_e32 v4, 1, v1
	v_cmp_ge_u32_e32 vcc, v3, v2
	v_add_u32_e32 v3, 1, v5
	s_nop 0
	v_cndmask_b32_e32 v1, v1, v4, vcc
	v_mul_lo_u32 v4, v2, v1
	v_add_u32_e32 v2, v4, v2
	v_cmp_ne_u32_e32 vcc, v3, v2
	s_and_saveexec_b64 s[4:5], vcc
	s_xor_b64 s[4:5], exec, s[4:5]
	s_cbranch_execz .LBB0_371
	s_waitcnt lgkmcnt(0)
	s_mov_b64 s[6:7], exec
	s_add_u32 s10, s96, 0x183500
	s_addc_u32 s11, s97, 0
	v_mov_b32_e32 v0, 0
	buffer_inv sc1
	s_mov_b32 s22, 0x100000
	global_load_dword v120, v0, s[10:11] sc1
	s_sleep 5
	global_load_dword v121, v0, s[10:11] sc1
	s_sleep 5
.Lpl_b2_loop:
	global_load_dword v122, v0, s[10:11] sc1
	s_waitcnt vmcnt(2)
	v_cmp_ne_u32_e32 vcc, v120, v1
	s_cbranch_vccnz .Lpl_b2_done
	s_sleep 5
	global_load_dword v120, v0, s[10:11] sc1
	s_waitcnt vmcnt(2)
	v_cmp_ne_u32_e32 vcc, v121, v1
	s_cbranch_vccnz .Lpl_b2_done
	s_sleep 5
	global_load_dword v121, v0, s[10:11] sc1
	s_waitcnt vmcnt(2)
	v_cmp_ne_u32_e32 vcc, v122, v1
	s_cbranch_vccnz .Lpl_b2_done
	s_sleep 5
	s_sub_i32 s22, s22, 1
	s_cmp_lg_u32 s22, 0
	s_cbranch_scc1 .Lpl_b2_loop
.Lpl_b2_done:
.LBB0_370:
	s_or_b64 exec, exec, s[6:7]
